# P0a: workgroup barrier per transpose item so the 8 waves issue their adjacent-column tile loads together (DRAM page locality test), on p0map
# baseline (speedup 1.0000x reference)
.LBB0_12:
	s_barrier
	s_cmpk_gt_i32 s4, 0x3c7f
	s_mov_b64 s[6:7], -1
	s_cbranch_scc0 .LBB0_77
	s_cmpk_gt_u32 s4, 0x427f
	s_cbranch_scc0 .LBB0_56
	s_cmpk_gt_u32 s4, 0x467f
	s_cbranch_scc0 .LBB0_35
	s_cmpk_gt_u32 s4, 0x667f
	s_cbranch_scc0 .LBB0_25
	s_cmpk_gt_u32 s4, 0xe67f
	s_cbranch_scc0 .LBB0_20
	s_add_i32 s62, s4, 0xffff1980
	s_load_dwordx2 s[8:9], s[12:13], 0xd0
	s_and_b32 s63, s62, 1
	s_lshl_b32 s63, s63, 7
	s_bfe_u32 s64, s62, 0x70001
	s_andn2_b32 s62, s62, 0xff
	s_or_b32 s62, s62, s63
	s_or_b32 s62, s62, s64
	s_lshr_b32 s6, s62, 1
	s_and_b32 s16, s6, 0x7fc0
	s_lshl_b32 s6, s62, 5
	s_and_b32 s6, s6, 0xfe0
	s_waitcnt lgkmcnt(0)
	s_lshl_b32 s10, s6, 2
	s_waitcnt lgkmcnt(0)
	s_add_u32 s8, s8, s10
	s_addc_u32 s9, s9, 0
	v_mov_b32_e32 v61, v35
	s_mov_b32 s7, 1
	v_lshl_add_u64 v[2:3], s[8:9], 0, v[60:61]
	v_or_b32_e32 v5, s16, v1
	v_or_b32_e32 v4, s16, v38
	s_mov_b32 s8, 0
	s_mov_b32 s9, 32
